# final LayerNorm output stores made plain instead of write-through (end-of-kernel release writes them back)
# baseline (speedup 1.0000x reference)
; __device__ __forceinline__ float bf_lo(unsigned w) { return __uint_as_float(w << 16); }
; __device__ __forceinline__ float bf_hi(unsigned w) { return __uint_as_float(w & 0xffff0000u); }
; #define GAS __attribute__((address_space(1)))
; __device__ __forceinline__ void st16_wt(void* p, f32x4 v) { asm volatile("global_store_dwordx4 %0, %1, off sc1\n\ts_nop 1" :: "v"(p), "v"(v) : "memory"); }
; __device__ __forceinline__ void p_final_ln(const Frame& F0, const Args& a) {
;     ...
;     for (int m0 = gw; m0 < MT; m0 += 8 * NGW) {
;         v2u v[8][4]; float rA[8], rB[8];
; #pragma unroll
;         for (int q = 0; q < 8; ++q) { const int m = m0 + q * NGW < MT ? m0 + q * NGW : MT - 1; pg8::ln_row(st, m, rA[q], rB[q]);
;             const GAS v2u* xr = (const GAS v2u*)(Z + (size_t)m * D) + F.lane;
; #pragma unroll
;             for (int j = 0; j < 4; ++j) v[q][j] = __builtin_nontemporal_load(xr + 64 * j); }
; #pragma unroll
;         for (int q = 0; q < 8; ++q) { const int m = m0 + q * NGW; if (m < MT) { GAS f32x4* xr = (GAS f32x4*)(a.out + (size_t)m * D) + F.lane;
; #pragma unroll
;             for (int j = 0; j < 4; ++j) { const f32x4 x = {pg8::bf_lo(v[q][j].x), pg8::bf_hi(v[q][j].x), pg8::bf_lo(v[q][j].y), pg8::bf_hi(v[q][j].y)}; st16_wt((void*)(xr + 64 * j), (x * rA[q] + rB[q]) * wv[j] + bv[j]); } } }
.LBB0_1825:
	s_add_i32 s21, s74, s58
	s_min_i32 s22, s21, 0x407f
	s_ashr_i32 s23, s22, 31
	s_lshl_b64 s[24:25], s[22:23], 3
	s_add_u32 s34, s13, s24
	s_addc_u32 s35, s33, s25
	s_add_i32 s30, s74, s52
	s_lshl_b64 s[38:39], s[22:23], 11
	s_min_i32 s22, s30, 0x407f
	s_ashr_i32 s23, s22, 31
	s_lshl_b64 s[24:25], s[22:23], 3
	s_add_u32 s36, s13, s24
	s_addc_u32 s37, s33, s25
	s_add_i32 s28, s74, s53
	s_lshl_b64 s[40:41], s[22:23], 11
	s_min_i32 s22, s28, 0x407f
	s_ashr_i32 s23, s22, 31
	s_lshl_b64 s[24:25], s[22:23], 3
	s_add_u32 s42, s13, s24
	s_addc_u32 s43, s33, s25
	s_add_i32 s26, s74, s55
	s_lshl_b64 s[46:47], s[22:23], 11
	s_min_i32 s22, s26, 0x407f
	s_ashr_i32 s23, s22, 31
	s_lshl_b64 s[24:25], s[22:23], 3
	s_add_u32 s48, s13, s24
	s_addc_u32 s49, s33, s25
	s_add_i32 s24, s74, s56
	s_lshl_b64 s[60:61], s[22:23], 11
	s_min_i32 s22, s24, 0x407f
	s_ashr_i32 s23, s22, 31
	s_lshl_b64 s[44:45], s[22:23], 3
	s_add_u32 s44, s13, s44
	s_addc_u32 s45, s33, s45
	s_lshl_b64 s[62:63], s[22:23], 11
	s_add_i32 s22, s74, s57
	s_min_i32 s64, s22, 0x407f
	s_ashr_i32 s65, s64, 31
	s_lshl_b64 s[66:67], s[64:65], 3
	s_add_u32 s66, s13, s66
	s_addc_u32 s67, s33, s67
	s_add_i32 s20, s74, s54
	s_min_i32 s68, s20, 0x407f
	s_ashr_i32 s69, s68, 31
	s_lshl_b64 s[64:65], s[64:65], 11
	s_lshl_b64 s[70:71], s[68:69], 3
	s_add_u32 s70, s13, s70
	s_addc_u32 s71, s33, s71
	s_lshl_b64 s[68:69], s[68:69], 11
	s_waitcnt vmcnt(3)
	v_lshl_add_u64 v[40:41], s[10:11], 0, v[38:39]
	v_add_co_u32_e32 v40, vcc, s59, v40
	s_add_u32 s72, s10, s50
	s_nop 0
	v_addc_co_u32_e32 v41, vcc, 0, v41, vcc
	s_addc_u32 s73, s11, s51
	global_load_dwordx2 v[110:111], v[40:41], off nt
	global_load_dwordx2 v[118:119], v[40:41], off offset:1536 nt
	global_load_dwordx2 v[120:121], v[40:41], off offset:1024 nt
	global_load_dwordx2 v[112:113], v[40:41], off offset:512 nt
	global_load_dwordx2 v[114:115], v33, s[72:73]
	v_lshl_add_u64 v[40:41], v[34:35], 0, s[38:39]
	global_load_dwordx2 v[106:107], v[40:41], off nt
	global_load_dwordx2 v[104:105], v[40:41], off offset:512 nt
	global_load_dwordx2 v[102:103], v[40:41], off offset:1024 nt
	global_load_dwordx2 v[100:101], v[40:41], off offset:1536 nt
	v_lshl_add_u64 v[40:41], v[34:35], 0, s[40:41]
	global_load_dwordx2 v[96:97], v[40:41], off nt
	global_load_dwordx2 v[94:95], v[40:41], off offset:512 nt
	global_load_dwordx2 v[92:93], v[40:41], off offset:1024 nt
	global_load_dwordx2 v[90:91], v[40:41], off offset:1536 nt
	v_lshl_add_u64 v[40:41], v[34:35], 0, s[46:47]
	global_load_dwordx2 v[86:87], v[40:41], off nt
	global_load_dwordx2 v[84:85], v[40:41], off offset:512 nt
	global_load_dwordx2 v[82:83], v[40:41], off offset:1024 nt
	global_load_dwordx2 v[80:81], v[40:41], off offset:1536 nt
	global_load_dwordx2 v[108:109], v33, s[34:35]
	global_load_dwordx2 v[98:99], v33, s[36:37]
	global_load_dwordx2 v[88:89], v33, s[42:43]
	global_load_dwordx2 v[78:79], v33, s[48:49]
	v_lshl_add_u64 v[40:41], v[34:35], 0, s[60:61]
	global_load_dwordx2 v[76:77], v[40:41], off nt
	global_load_dwordx2 v[74:75], v[40:41], off offset:512 nt
	global_load_dwordx2 v[72:73], v[40:41], off offset:1024 nt
	global_load_dwordx2 v[70:71], v[40:41], off offset:1536 nt
	v_lshl_add_u64 v[40:41], v[34:35], 0, s[62:63]
	global_load_dwordx2 v[66:67], v[40:41], off nt
	global_load_dwordx2 v[64:65], v[40:41], off offset:512 nt
	global_load_dwordx2 v[62:63], v[40:41], off offset:1024 nt
	global_load_dwordx2 v[60:61], v[40:41], off offset:1536 nt
	v_lshl_add_u64 v[40:41], v[34:35], 0, s[64:65]
	v_lshl_add_u64 v[116:117], v[34:35], 0, s[68:69]
	global_load_dwordx2 v[56:57], v[40:41], off nt
	global_load_dwordx2 v[54:55], v[40:41], off offset:512 nt
	global_load_dwordx2 v[52:53], v[40:41], off offset:1024 nt
	global_load_dwordx2 v[50:51], v[40:41], off offset:1536 nt
	global_load_dwordx2 v[46:47], v[116:117], off nt
	global_load_dwordx2 v[44:45], v[116:117], off offset:512 nt
	global_load_dwordx2 v[42:43], v[116:117], off offset:1024 nt
	s_nop 0
	global_load_dwordx2 v[40:41], v[116:117], off offset:1536 nt
	global_load_dwordx2 v[68:69], v33, s[44:45]
	global_load_dwordx2 v[58:59], v33, s[66:67]
	global_load_dwordx2 v[48:49], v33, s[70:71]
	v_lshl_add_u64 v[122:123], s[0:1], 0, v[32:33]
	v_lshl_add_u64 v[124:125], v[122:123], 0, s[14:15]
	s_cmpk_gt_i32 s21, 0x407f
	s_waitcnt vmcnt(37)
	v_lshlrev_b32_e32 v130, 16, v120
	v_lshlrev_b32_e32 v116, 16, v110
	s_waitcnt vmcnt(35)
	v_pk_mul_f32 v[114:115], v[114:115], s[12:13] op_sel_hi:[1,0]
	v_and_b32_e32 v117, 0xffff0000, v110
	v_fma_f32 v115, -v114, v114, v115
	v_max_f32_e32 v115, 0, v115
	v_add_f32_e32 v115, 0x3727c5ac, v115
	v_rsq_f32_e32 v128, v115
	v_lshlrev_b32_e32 v110, 16, v111
	v_and_b32_e32 v111, 0xffff0000, v111
	v_and_b32_e32 v131, 0xffff0000, v120
	v_mul_f32_e64 v120, v114, -v128
	v_lshlrev_b32_e32 v126, 16, v112
	v_and_b32_e32 v127, 0xffff0000, v112
	v_lshlrev_b32_e32 v112, 16, v113
	v_and_b32_e32 v113, 0xffff0000, v113
	v_pk_fma_f32 v[114:115], v[128:129], v[116:117], v[120:121] op_sel_hi:[0,1,0]
	v_pk_fma_f32 v[110:111], v[128:129], v[110:111], v[120:121] op_sel_hi:[0,1,0]
	v_pk_fma_f32 v[116:117], v[128:129], v[112:113], v[120:121] op_sel_hi:[0,1,0]
	v_pk_fma_f32 v[112:113], v[2:3], v[110:111], v[6:7]
	v_pk_fma_f32 v[110:111], v[0:1], v[114:115], v[4:5]
	v_pk_fma_f32 v[126:127], v[128:129], v[126:127], v[120:121] op_sel_hi:[0,1,0]
	v_pk_fma_f32 v[116:117], v[10:11], v[116:117], v[18:19]
	global_store_dwordx4 v[122:123], v[110:113], off
	s_nop 1
	v_lshlrev_b32_e32 v110, 16, v121
	v_and_b32_e32 v111, 0xffff0000, v121
	v_pk_fma_f32 v[114:115], v[8:9], v[126:127], v[16:17]
	v_pk_fma_f32 v[110:111], v[128:129], v[110:111], v[120:121] op_sel_hi:[0,1,0]
	global_store_dwordx4 v[124:125], v[114:117], off
	s_nop 1
	v_pk_fma_f32 v[116:117], v[128:129], v[130:131], v[120:121] op_sel_hi:[0,1,0]
	v_pk_fma_f32 v[112:113], v[14:15], v[110:111], v[22:23]
	v_pk_fma_f32 v[110:111], v[12:13], v[116:117], v[20:21]
	v_lshl_add_u64 v[114:115], v[122:123], 0, s[16:17]
	global_store_dwordx4 v[114:115], v[110:113], off
	s_nop 1
	v_lshlrev_b32_e32 v110, 16, v118
	v_and_b32_e32 v111, 0xffff0000, v118
	v_lshlrev_b32_e32 v112, 16, v119
	v_and_b32_e32 v113, 0xffff0000, v119
	v_pk_fma_f32 v[110:111], v[128:129], v[110:111], v[120:121] op_sel_hi:[0,1,0]
	v_pk_fma_f32 v[112:113], v[128:129], v[112:113], v[120:121] op_sel_hi:[0,1,0]
	v_lshl_add_u64 v[114:115], v[122:123], 0, s[18:19]
	v_pk_fma_f32 v[112:113], v[26:27], v[112:113], v[30:31]
	v_pk_fma_f32 v[110:111], v[24:25], v[110:111], v[28:29]
	s_nop 0
	global_store_dwordx4 v[114:115], v[110:113], off
	s_nop 1
	s_cbranch_scc1 .LBB0_1832
; __device__ __forceinline__ float bf_lo(unsigned w) { return __uint_as_float(w << 16); }
; __device__ __forceinline__ float bf_hi(unsigned w) { return __uint_as_float(w & 0xffff0000u); }
; #define GAS __attribute__((address_space(1)))
; __device__ __forceinline__ void st16_wt(void* p, f32x4 v) { asm volatile("global_store_dwordx4 %0, %1, off sc1\n\ts_nop 1" :: "v"(p), "v"(v) : "memory"); }
; __device__ __forceinline__ void p_final_ln(const Frame& F0, const Args& a) {
;     ...
;         for (int q = 0; q < 8; ++q) { const int m = m0 + q * NGW; if (m < MT) { GAS f32x4* xr = (GAS f32x4*)(a.out + (size_t)m * D) + F.lane;
; #pragma unroll
;             for (int j = 0; j < 4; ++j) { const f32x4 x = {pg8::bf_lo(v[q][j].x), pg8::bf_hi(v[q][j].x), pg8::bf_lo(v[q][j].y), pg8::bf_hi(v[q][j].y)}; st16_wt((void*)(xr + 64 * j), (x * rA[q] + rB[q]) * wv[j] + bv[j]); } } }
	s_waitcnt vmcnt(22)
	v_pk_mul_f32 v[108:109], v[108:109], s[12:13] op_sel_hi:[1,0]
	v_lshlrev_b32_e32 v114, 16, v106
	v_fma_f32 v109, -v108, v108, v109
	v_max_f32_e32 v109, 0, v109
	v_add_f32_e32 v109, 0x3727c5ac, v109
	v_rsq_f32_e32 v110, v109
	v_and_b32_e32 v115, 0xffff0000, v106
	v_lshlrev_b32_e32 v106, 16, v107
	v_and_b32_e32 v107, 0xffff0000, v107
	v_mul_f32_e64 v116, v108, -v110
	v_pk_fma_f32 v[114:115], v[110:111], v[114:115], v[116:117] op_sel_hi:[0,1,0]
	v_pk_fma_f32 v[106:107], v[110:111], v[106:107], v[116:117] op_sel_hi:[0,1,0]
	v_pk_fma_f32 v[108:109], v[2:3], v[106:107], v[6:7]
	v_pk_fma_f32 v[106:107], v[0:1], v[114:115], v[4:5]
	v_lshl_add_u64 v[112:113], s[8:9], 0, v[32:33]
	global_store_dwordx4 v[112:113], v[106:109], off
	s_nop 1
	v_lshlrev_b32_e32 v106, 16, v104
	v_and_b32_e32 v107, 0xffff0000, v104
	v_lshlrev_b32_e32 v104, 16, v105
	v_and_b32_e32 v105, 0xffff0000, v105
	v_pk_fma_f32 v[114:115], v[110:111], v[106:107], v[116:117] op_sel_hi:[0,1,0]
	v_pk_fma_f32 v[104:105], v[110:111], v[104:105], v[116:117] op_sel_hi:[0,1,0]
	v_pk_fma_f32 v[106:107], v[10:11], v[104:105], v[18:19]
	v_pk_fma_f32 v[104:105], v[8:9], v[114:115], v[16:17]
	v_lshl_add_u64 v[108:109], v[112:113], 0, s[14:15]
	global_store_dwordx4 v[108:109], v[104:107], off
	s_nop 1
	v_lshlrev_b32_e32 v104, 16, v102
	v_and_b32_e32 v105, 0xffff0000, v102
	v_lshlrev_b32_e32 v102, 16, v103
	v_and_b32_e32 v103, 0xffff0000, v103
	v_pk_fma_f32 v[108:109], v[110:111], v[104:105], v[116:117] op_sel_hi:[0,1,0]
	v_pk_fma_f32 v[102:103], v[110:111], v[102:103], v[116:117] op_sel_hi:[0,1,0]
	v_pk_fma_f32 v[104:105], v[14:15], v[102:103], v[22:23]
	v_pk_fma_f32 v[102:103], v[12:13], v[108:109], v[20:21]
	v_lshl_add_u64 v[106:107], v[112:113], 0, s[16:17]
	global_store_dwordx4 v[106:107], v[102:105], off
	s_nop 1
	v_lshlrev_b32_e32 v102, 16, v100
	v_and_b32_e32 v103, 0xffff0000, v100
	v_lshlrev_b32_e32 v100, 16, v101
	v_and_b32_e32 v101, 0xffff0000, v101
	v_pk_fma_f32 v[106:107], v[110:111], v[102:103], v[116:117] op_sel_hi:[0,1,0]
	v_pk_fma_f32 v[100:101], v[110:111], v[100:101], v[116:117] op_sel_hi:[0,1,0]
	v_lshl_add_u64 v[104:105], v[112:113], 0, s[18:19]
	v_pk_fma_f32 v[102:103], v[26:27], v[100:101], v[30:31]
	v_pk_fma_f32 v[100:101], v[24:25], v[106:107], v[28:29]
	s_nop 0
	global_store_dwordx4 v[104:105], v[100:103], off
	s_nop 1
	s_add_i32 s21, s92, s21
	s_cmpk_gt_i32 s21, 0x407f
	s_cbranch_scc0 .LBB0_1833

; __device__ __forceinline__ float bf_lo(unsigned w) { return __uint_as_float(w << 16); }
; __device__ __forceinline__ float bf_hi(unsigned w) { return __uint_as_float(w & 0xffff0000u); }
; #define GAS __attribute__((address_space(1)))
; __device__ __forceinline__ void st16_wt(void* p, f32x4 v) { asm volatile("global_store_dwordx4 %0, %1, off sc1\n\ts_nop 1" :: "v"(p), "v"(v) : "memory"); }
; __device__ __forceinline__ void p_final_ln(const Frame& F0, const Args& a) {
;     ...
;         for (int q = 0; q < 8; ++q) { const int m = m0 + q * NGW; if (m < MT) { GAS f32x4* xr = (GAS f32x4*)(a.out + (size_t)m * D) + F.lane;
; #pragma unroll
;             for (int j = 0; j < 4; ++j) { const f32x4 x = {pg8::bf_lo(v[q][j].x), pg8::bf_hi(v[q][j].x), pg8::bf_lo(v[q][j].y), pg8::bf_hi(v[q][j].y)}; st16_wt((void*)(xr + 64 * j), (x * rA[q] + rB[q]) * wv[j] + bv[j]); } } }
.LBB0_1828:
	s_waitcnt vmcnt(20)
	v_mul_f32_e32 v88, 0x3a800000, v88
	v_mul_f32_e32 v90, v88, v88
	v_fma_f32 v89, v89, s12, -v90
	v_max_f32_e32 v89, 0, v89
	v_add_f32_e32 v89, 0x3727c5ac, v89
	v_rsq_f32_e32 v90, v89
	v_and_b32_e32 v89, 0xffff0000, v86
	s_ashr_i32 s29, s28, 31
	s_lshl_b64 s[28:29], s[28:29], 12
	v_mul_f32_e64 v94, v88, -v90
	v_lshlrev_b32_e32 v88, 16, v86
	v_lshlrev_b32_e32 v86, 16, v87
	v_and_b32_e32 v87, 0xffff0000, v87
	v_pk_fma_f32 v[96:97], v[90:91], v[88:89], v[94:95] op_sel_hi:[0,1,0]
	v_pk_fma_f32 v[86:87], v[90:91], v[86:87], v[94:95] op_sel_hi:[0,1,0]
	v_pk_fma_f32 v[88:89], v[2:3], v[86:87], v[6:7]
	v_pk_fma_f32 v[86:87], v[0:1], v[96:97], v[4:5]
	v_lshl_add_u64 v[92:93], v[36:37], 0, s[28:29]
	global_store_dwordx4 v[92:93], v[86:89], off
	s_nop 1
	v_lshlrev_b32_e32 v86, 16, v84
	v_and_b32_e32 v87, 0xffff0000, v84
	v_lshlrev_b32_e32 v84, 16, v85
	v_and_b32_e32 v85, 0xffff0000, v85
	v_pk_fma_f32 v[96:97], v[90:91], v[86:87], v[94:95] op_sel_hi:[0,1,0]
	v_pk_fma_f32 v[84:85], v[90:91], v[84:85], v[94:95] op_sel_hi:[0,1,0]
	v_pk_fma_f32 v[86:87], v[10:11], v[84:85], v[18:19]
	v_pk_fma_f32 v[84:85], v[8:9], v[96:97], v[16:17]
	v_lshl_add_u64 v[88:89], v[92:93], 0, s[14:15]
	global_store_dwordx4 v[88:89], v[84:87], off
	s_nop 1
	v_lshlrev_b32_e32 v84, 16, v82
	v_and_b32_e32 v85, 0xffff0000, v82
	v_lshlrev_b32_e32 v82, 16, v83
	v_and_b32_e32 v83, 0xffff0000, v83
	v_pk_fma_f32 v[88:89], v[90:91], v[84:85], v[94:95] op_sel_hi:[0,1,0]
	v_pk_fma_f32 v[82:83], v[90:91], v[82:83], v[94:95] op_sel_hi:[0,1,0]
	v_pk_fma_f32 v[84:85], v[14:15], v[82:83], v[22:23]
	v_pk_fma_f32 v[82:83], v[12:13], v[88:89], v[20:21]
	v_lshl_add_u64 v[86:87], v[92:93], 0, s[16:17]
	global_store_dwordx4 v[86:87], v[82:85], off
	s_nop 1
	v_lshlrev_b32_e32 v82, 16, v80
	v_and_b32_e32 v83, 0xffff0000, v80
	v_lshlrev_b32_e32 v80, 16, v81
	v_and_b32_e32 v81, 0xffff0000, v81
	v_pk_fma_f32 v[86:87], v[90:91], v[82:83], v[94:95] op_sel_hi:[0,1,0]
	v_pk_fma_f32 v[80:81], v[90:91], v[80:81], v[94:95] op_sel_hi:[0,1,0]
	v_lshl_add_u64 v[84:85], v[92:93], 0, s[18:19]
	v_pk_fma_f32 v[82:83], v[26:27], v[80:81], v[30:31]
	v_pk_fma_f32 v[80:81], v[24:25], v[86:87], v[28:29]
	s_nop 0
	global_store_dwordx4 v[84:85], v[80:83], off
	s_nop 1
	s_add_i32 s21, s92, s21
	s_cmpk_gt_i32 s21, 0x407f
	s_cbranch_scc0 .LBB0_1835

; __device__ __forceinline__ float bf_lo(unsigned w) { return __uint_as_float(w << 16); }
; __device__ __forceinline__ float bf_hi(unsigned w) { return __uint_as_float(w & 0xffff0000u); }
; #define GAS __attribute__((address_space(1)))
; __device__ __forceinline__ void st16_wt(void* p, f32x4 v) { asm volatile("global_store_dwordx4 %0, %1, off sc1\n\ts_nop 1" :: "v"(p), "v"(v) : "memory"); }
; __device__ __forceinline__ void p_final_ln(const Frame& F0, const Args& a) {
;     ...
;         for (int q = 0; q < 8; ++q) { const int m = m0 + q * NGW; if (m < MT) { GAS f32x4* xr = (GAS f32x4*)(a.out + (size_t)m * D) + F.lane;
; #pragma unroll
;             for (int j = 0; j < 4; ++j) { const f32x4 x = {pg8::bf_lo(v[q][j].x), pg8::bf_hi(v[q][j].x), pg8::bf_lo(v[q][j].y), pg8::bf_hi(v[q][j].y)}; st16_wt((void*)(xr + 64 * j), (x * rA[q] + rB[q]) * wv[j] + bv[j]); } } }
.LBB0_1830:
	s_waitcnt vmcnt(2)
	v_mul_f32_e32 v68, 0x3a800000, v68
	v_mul_f32_e32 v70, v68, v68
	v_fma_f32 v69, v69, s12, -v70
	v_max_f32_e32 v69, 0, v69
	v_add_f32_e32 v69, 0x3727c5ac, v69
	v_rsq_f32_e32 v70, v69
	v_and_b32_e32 v69, 0xffff0000, v66
	s_ashr_i32 s25, s24, 31
	s_lshl_b64 s[24:25], s[24:25], 12
	v_mul_f32_e64 v74, v68, -v70
	v_lshlrev_b32_e32 v68, 16, v66
	v_lshlrev_b32_e32 v66, 16, v67
	v_and_b32_e32 v67, 0xffff0000, v67
	v_pk_fma_f32 v[76:77], v[70:71], v[68:69], v[74:75] op_sel_hi:[0,1,0]
	v_pk_fma_f32 v[66:67], v[70:71], v[66:67], v[74:75] op_sel_hi:[0,1,0]
	v_pk_fma_f32 v[68:69], v[2:3], v[66:67], v[6:7]
	v_pk_fma_f32 v[66:67], v[0:1], v[76:77], v[4:5]
	v_lshl_add_u64 v[72:73], v[36:37], 0, s[24:25]
	global_store_dwordx4 v[72:73], v[66:69], off
	s_nop 1
	v_lshlrev_b32_e32 v66, 16, v64
	v_and_b32_e32 v67, 0xffff0000, v64
	v_lshlrev_b32_e32 v64, 16, v65
	v_and_b32_e32 v65, 0xffff0000, v65
	v_pk_fma_f32 v[76:77], v[70:71], v[66:67], v[74:75] op_sel_hi:[0,1,0]
	v_pk_fma_f32 v[64:65], v[70:71], v[64:65], v[74:75] op_sel_hi:[0,1,0]
	v_pk_fma_f32 v[66:67], v[10:11], v[64:65], v[18:19]
	v_pk_fma_f32 v[64:65], v[8:9], v[76:77], v[16:17]
	v_lshl_add_u64 v[68:69], v[72:73], 0, s[14:15]
	global_store_dwordx4 v[68:69], v[64:67], off
	s_nop 1
	v_lshlrev_b32_e32 v64, 16, v62
	v_and_b32_e32 v65, 0xffff0000, v62
	v_lshlrev_b32_e32 v62, 16, v63
	v_and_b32_e32 v63, 0xffff0000, v63
	v_pk_fma_f32 v[68:69], v[70:71], v[64:65], v[74:75] op_sel_hi:[0,1,0]
	v_pk_fma_f32 v[62:63], v[70:71], v[62:63], v[74:75] op_sel_hi:[0,1,0]
	v_pk_fma_f32 v[64:65], v[14:15], v[62:63], v[22:23]
	v_pk_fma_f32 v[62:63], v[12:13], v[68:69], v[20:21]
	v_lshl_add_u64 v[66:67], v[72:73], 0, s[16:17]
	global_store_dwordx4 v[66:67], v[62:65], off
	s_nop 1
	v_lshlrev_b32_e32 v62, 16, v60
	v_and_b32_e32 v63, 0xffff0000, v60
	v_lshlrev_b32_e32 v60, 16, v61
	v_and_b32_e32 v61, 0xffff0000, v61
	v_pk_fma_f32 v[66:67], v[70:71], v[62:63], v[74:75] op_sel_hi:[0,1,0]
	v_pk_fma_f32 v[60:61], v[70:71], v[60:61], v[74:75] op_sel_hi:[0,1,0]
	v_lshl_add_u64 v[64:65], v[72:73], 0, s[18:19]
	v_pk_fma_f32 v[62:63], v[26:27], v[60:61], v[30:31]
	v_pk_fma_f32 v[60:61], v[24:25], v[66:67], v[28:29]
	s_nop 0
	global_store_dwordx4 v[64:65], v[60:63], off
	s_nop 1
	s_add_i32 s21, s92, s21
	s_cmpk_gt_i32 s21, 0x407f
	s_cbranch_scc0 .LBB0_1837

; __device__ __forceinline__ float bf_lo(unsigned w) { return __uint_as_float(w << 16); }
; __device__ __forceinline__ float bf_hi(unsigned w) { return __uint_as_float(w & 0xffff0000u); }
; #define GAS __attribute__((address_space(1)))
; __device__ __forceinline__ void st16_wt(void* p, f32x4 v) { asm volatile("global_store_dwordx4 %0, %1, off sc1\n\ts_nop 1" :: "v"(p), "v"(v) : "memory"); }
; __device__ __forceinline__ void p_final_ln(const Frame& F0, const Args& a) {
;     ...
;         for (int q = 0; q < 8; ++q) { const int m = m0 + q * NGW; if (m < MT) { GAS f32x4* xr = (GAS f32x4*)(a.out + (size_t)m * D) + F.lane;
; #pragma unroll
;             for (int j = 0; j < 4; ++j) { const f32x4 x = {pg8::bf_lo(v[q][j].x), pg8::bf_hi(v[q][j].x), pg8::bf_lo(v[q][j].y), pg8::bf_hi(v[q][j].y)}; st16_wt((void*)(xr + 64 * j), (x * rA[q] + rB[q]) * wv[j] + bv[j]); } } }
.LBB0_1833:
	s_waitcnt vmcnt(21)
	v_mul_f32_e32 v98, 0x3a800000, v98
	v_mul_f32_e32 v100, v98, v98
	v_fma_f32 v99, v99, s12, -v100
	v_max_f32_e32 v99, 0, v99
	v_add_f32_e32 v99, 0x3727c5ac, v99
	v_rsq_f32_e32 v100, v99
	v_and_b32_e32 v99, 0xffff0000, v96
	s_ashr_i32 s31, s30, 31
	s_lshl_b64 s[30:31], s[30:31], 12
	v_mul_f32_e64 v104, v98, -v100
	v_lshlrev_b32_e32 v98, 16, v96
	v_lshlrev_b32_e32 v96, 16, v97
	v_and_b32_e32 v97, 0xffff0000, v97
	v_pk_fma_f32 v[106:107], v[100:101], v[98:99], v[104:105] op_sel_hi:[0,1,0]
	v_pk_fma_f32 v[96:97], v[100:101], v[96:97], v[104:105] op_sel_hi:[0,1,0]
	v_pk_fma_f32 v[98:99], v[2:3], v[96:97], v[6:7]
	v_pk_fma_f32 v[96:97], v[0:1], v[106:107], v[4:5]
	v_lshl_add_u64 v[102:103], v[36:37], 0, s[30:31]
	global_store_dwordx4 v[102:103], v[96:99], off
	s_nop 1
	v_lshlrev_b32_e32 v96, 16, v94
	v_and_b32_e32 v97, 0xffff0000, v94
	v_lshlrev_b32_e32 v94, 16, v95
	v_and_b32_e32 v95, 0xffff0000, v95
	v_pk_fma_f32 v[106:107], v[100:101], v[96:97], v[104:105] op_sel_hi:[0,1,0]
	v_pk_fma_f32 v[94:95], v[100:101], v[94:95], v[104:105] op_sel_hi:[0,1,0]
	v_pk_fma_f32 v[96:97], v[10:11], v[94:95], v[18:19]
	v_pk_fma_f32 v[94:95], v[8:9], v[106:107], v[16:17]
	v_lshl_add_u64 v[98:99], v[102:103], 0, s[14:15]
	global_store_dwordx4 v[98:99], v[94:97], off
	s_nop 1
	v_lshlrev_b32_e32 v94, 16, v92
	v_and_b32_e32 v95, 0xffff0000, v92
	v_lshlrev_b32_e32 v92, 16, v93
	v_and_b32_e32 v93, 0xffff0000, v93
	v_pk_fma_f32 v[98:99], v[100:101], v[94:95], v[104:105] op_sel_hi:[0,1,0]
	v_pk_fma_f32 v[92:93], v[100:101], v[92:93], v[104:105] op_sel_hi:[0,1,0]
	v_pk_fma_f32 v[94:95], v[14:15], v[92:93], v[22:23]
	v_pk_fma_f32 v[92:93], v[12:13], v[98:99], v[20:21]
	v_lshl_add_u64 v[96:97], v[102:103], 0, s[16:17]
	global_store_dwordx4 v[96:97], v[92:95], off
	s_nop 1
	v_lshlrev_b32_e32 v92, 16, v90
	v_and_b32_e32 v93, 0xffff0000, v90
	v_lshlrev_b32_e32 v90, 16, v91
	v_and_b32_e32 v91, 0xffff0000, v91
	v_pk_fma_f32 v[96:97], v[100:101], v[92:93], v[104:105] op_sel_hi:[0,1,0]
	v_pk_fma_f32 v[90:91], v[100:101], v[90:91], v[104:105] op_sel_hi:[0,1,0]
	v_lshl_add_u64 v[94:95], v[102:103], 0, s[18:19]
	v_pk_fma_f32 v[92:93], v[26:27], v[90:91], v[30:31]
	v_pk_fma_f32 v[90:91], v[24:25], v[96:97], v[28:29]
	s_nop 0
	global_store_dwordx4 v[94:95], v[90:93], off
	s_nop 1
	s_add_i32 s21, s92, s21
	s_cmpk_gt_i32 s21, 0x407f
	s_cbranch_scc0 .LBB0_1828

; __device__ __forceinline__ float bf_lo(unsigned w) { return __uint_as_float(w << 16); }
; __device__ __forceinline__ float bf_hi(unsigned w) { return __uint_as_float(w & 0xffff0000u); }
; #define GAS __attribute__((address_space(1)))
; __device__ __forceinline__ void st16_wt(void* p, f32x4 v) { asm volatile("global_store_dwordx4 %0, %1, off sc1\n\ts_nop 1" :: "v"(p), "v"(v) : "memory"); }
; __device__ __forceinline__ void p_final_ln(const Frame& F0, const Args& a) {
;     ...
;         for (int q = 0; q < 8; ++q) { const int m = m0 + q * NGW; if (m < MT) { GAS f32x4* xr = (GAS f32x4*)(a.out + (size_t)m * D) + F.lane;
; #pragma unroll
;             for (int j = 0; j < 4; ++j) { const f32x4 x = {pg8::bf_lo(v[q][j].x), pg8::bf_hi(v[q][j].x), pg8::bf_lo(v[q][j].y), pg8::bf_hi(v[q][j].y)}; st16_wt((void*)(xr + 64 * j), (x * rA[q] + rB[q]) * wv[j] + bv[j]); } } }
.LBB0_1835:
	s_waitcnt vmcnt(19)
	v_mul_f32_e32 v78, 0x3a800000, v78
	v_mul_f32_e32 v80, v78, v78
	v_fma_f32 v79, v79, s12, -v80
	v_max_f32_e32 v79, 0, v79
	v_add_f32_e32 v79, 0x3727c5ac, v79
	v_rsq_f32_e32 v80, v79
	s_waitcnt vmcnt(18)
	v_and_b32_e32 v79, 0xffff0000, v76
	s_ashr_i32 s27, s26, 31
	s_lshl_b64 s[26:27], s[26:27], 12
	v_mul_f32_e64 v84, v78, -v80
	v_lshlrev_b32_e32 v78, 16, v76
	v_lshlrev_b32_e32 v76, 16, v77
	v_and_b32_e32 v77, 0xffff0000, v77
	v_pk_fma_f32 v[86:87], v[80:81], v[78:79], v[84:85] op_sel_hi:[0,1,0]
	v_pk_fma_f32 v[76:77], v[80:81], v[76:77], v[84:85] op_sel_hi:[0,1,0]
	v_pk_fma_f32 v[78:79], v[2:3], v[76:77], v[6:7]
	v_pk_fma_f32 v[76:77], v[0:1], v[86:87], v[4:5]
	v_lshl_add_u64 v[82:83], v[36:37], 0, s[26:27]
	global_store_dwordx4 v[82:83], v[76:79], off
	s_nop 1
	s_waitcnt vmcnt(17)
	v_lshlrev_b32_e32 v76, 16, v74
	v_and_b32_e32 v77, 0xffff0000, v74
	v_lshlrev_b32_e32 v74, 16, v75
	v_and_b32_e32 v75, 0xffff0000, v75
	v_pk_fma_f32 v[86:87], v[80:81], v[76:77], v[84:85] op_sel_hi:[0,1,0]
	v_pk_fma_f32 v[74:75], v[80:81], v[74:75], v[84:85] op_sel_hi:[0,1,0]
	v_pk_fma_f32 v[76:77], v[10:11], v[74:75], v[18:19]
	v_pk_fma_f32 v[74:75], v[8:9], v[86:87], v[16:17]
	v_lshl_add_u64 v[78:79], v[82:83], 0, s[14:15]
	global_store_dwordx4 v[78:79], v[74:77], off
	s_nop 1
	s_waitcnt vmcnt(16)
	v_lshlrev_b32_e32 v74, 16, v72
	v_and_b32_e32 v75, 0xffff0000, v72
	v_lshlrev_b32_e32 v72, 16, v73
	v_and_b32_e32 v73, 0xffff0000, v73
	v_pk_fma_f32 v[78:79], v[80:81], v[74:75], v[84:85] op_sel_hi:[0,1,0]
	v_pk_fma_f32 v[72:73], v[80:81], v[72:73], v[84:85] op_sel_hi:[0,1,0]
	v_pk_fma_f32 v[74:75], v[14:15], v[72:73], v[22:23]
	v_pk_fma_f32 v[72:73], v[12:13], v[78:79], v[20:21]
	v_lshl_add_u64 v[76:77], v[82:83], 0, s[16:17]
	global_store_dwordx4 v[76:77], v[72:75], off
	s_nop 1
	s_waitcnt vmcnt(15)
	v_lshlrev_b32_e32 v72, 16, v70
	v_and_b32_e32 v73, 0xffff0000, v70
	v_lshlrev_b32_e32 v70, 16, v71
	v_and_b32_e32 v71, 0xffff0000, v71
	v_pk_fma_f32 v[76:77], v[80:81], v[72:73], v[84:85] op_sel_hi:[0,1,0]
	v_pk_fma_f32 v[70:71], v[80:81], v[70:71], v[84:85] op_sel_hi:[0,1,0]
	v_lshl_add_u64 v[74:75], v[82:83], 0, s[18:19]
	v_pk_fma_f32 v[72:73], v[26:27], v[70:71], v[30:31]
	v_pk_fma_f32 v[70:71], v[24:25], v[76:77], v[28:29]
	s_nop 0
	global_store_dwordx4 v[74:75], v[70:73], off
	s_nop 1
	s_add_i32 s21, s92, s21
	s_cmpk_gt_i32 s21, 0x407f
	s_cbranch_scc0 .LBB0_1830

; __device__ __forceinline__ float bf_lo(unsigned w) { return __uint_as_float(w << 16); }
; __device__ __forceinline__ float bf_hi(unsigned w) { return __uint_as_float(w & 0xffff0000u); }
; #define GAS __attribute__((address_space(1)))
; __device__ __forceinline__ void st16_wt(void* p, f32x4 v) { asm volatile("global_store_dwordx4 %0, %1, off sc1\n\ts_nop 1" :: "v"(p), "v"(v) : "memory"); }
; __device__ __forceinline__ void p_final_ln(const Frame& F0, const Args& a) {
;     ...
;         for (int q = 0; q < 8; ++q) { const int m = m0 + q * NGW; if (m < MT) { GAS f32x4* xr = (GAS f32x4*)(a.out + (size_t)m * D) + F.lane;
; #pragma unroll
;             for (int j = 0; j < 4; ++j) { const f32x4 x = {pg8::bf_lo(v[q][j].x), pg8::bf_hi(v[q][j].x), pg8::bf_lo(v[q][j].y), pg8::bf_hi(v[q][j].y)}; st16_wt((void*)(xr + 64 * j), (x * rA[q] + rB[q]) * wv[j] + bv[j]); } } }
.LBB0_1837:
	s_waitcnt vmcnt(1)
	v_mul_f32_e32 v58, 0x3a800000, v58
	v_mul_f32_e32 v60, v58, v58
	v_fma_f32 v59, v59, s12, -v60
	v_max_f32_e32 v59, 0, v59
	v_add_f32_e32 v59, 0x3727c5ac, v59
	v_rsq_f32_e32 v60, v59
	v_and_b32_e32 v59, 0xffff0000, v56
	s_ashr_i32 s23, s22, 31
	s_lshl_b64 s[22:23], s[22:23], 12
	v_mul_f32_e64 v64, v58, -v60
	v_lshlrev_b32_e32 v58, 16, v56
	v_lshlrev_b32_e32 v56, 16, v57
	v_and_b32_e32 v57, 0xffff0000, v57
	v_pk_fma_f32 v[66:67], v[60:61], v[58:59], v[64:65] op_sel_hi:[0,1,0]
	v_pk_fma_f32 v[56:57], v[60:61], v[56:57], v[64:65] op_sel_hi:[0,1,0]
	v_pk_fma_f32 v[58:59], v[2:3], v[56:57], v[6:7]
	v_pk_fma_f32 v[56:57], v[0:1], v[66:67], v[4:5]
	v_lshl_add_u64 v[62:63], v[36:37], 0, s[22:23]
	global_store_dwordx4 v[62:63], v[56:59], off
	s_nop 1
	v_lshlrev_b32_e32 v56, 16, v54
	v_and_b32_e32 v57, 0xffff0000, v54
	v_lshlrev_b32_e32 v54, 16, v55
	v_and_b32_e32 v55, 0xffff0000, v55
	v_pk_fma_f32 v[66:67], v[60:61], v[56:57], v[64:65] op_sel_hi:[0,1,0]
	v_pk_fma_f32 v[54:55], v[60:61], v[54:55], v[64:65] op_sel_hi:[0,1,0]
	v_pk_fma_f32 v[56:57], v[10:11], v[54:55], v[18:19]
	v_pk_fma_f32 v[54:55], v[8:9], v[66:67], v[16:17]
	v_lshl_add_u64 v[58:59], v[62:63], 0, s[14:15]
	global_store_dwordx4 v[58:59], v[54:57], off
	s_nop 1
	v_lshlrev_b32_e32 v54, 16, v52
	v_and_b32_e32 v55, 0xffff0000, v52
	v_lshlrev_b32_e32 v52, 16, v53
	v_and_b32_e32 v53, 0xffff0000, v53
	v_pk_fma_f32 v[58:59], v[60:61], v[54:55], v[64:65] op_sel_hi:[0,1,0]
	v_pk_fma_f32 v[52:53], v[60:61], v[52:53], v[64:65] op_sel_hi:[0,1,0]
	v_pk_fma_f32 v[54:55], v[14:15], v[52:53], v[22:23]
	v_pk_fma_f32 v[52:53], v[12:13], v[58:59], v[20:21]
	v_lshl_add_u64 v[56:57], v[62:63], 0, s[16:17]
	global_store_dwordx4 v[56:57], v[52:55], off
	s_nop 1
	v_lshlrev_b32_e32 v52, 16, v50
	v_and_b32_e32 v53, 0xffff0000, v50
	v_lshlrev_b32_e32 v50, 16, v51
	v_and_b32_e32 v51, 0xffff0000, v51
	v_pk_fma_f32 v[56:57], v[60:61], v[52:53], v[64:65] op_sel_hi:[0,1,0]
	v_pk_fma_f32 v[50:51], v[60:61], v[50:51], v[64:65] op_sel_hi:[0,1,0]
	v_lshl_add_u64 v[54:55], v[62:63], 0, s[18:19]
	v_pk_fma_f32 v[52:53], v[26:27], v[50:51], v[30:31]
	v_pk_fma_f32 v[50:51], v[24:25], v[56:57], v[28:29]
	s_nop 0
	global_store_dwordx4 v[54:55], v[50:53], off
	s_nop 1
	s_add_i32 s22, s92, s21
	s_cmpk_gt_i32 s22, 0x407f
	s_cbranch_scc1 .LBB0_1824
.LBB0_1838:
	s_waitcnt vmcnt(0)
	v_mul_f32_e32 v48, 0x3a800000, v48
	v_mul_f32_e32 v50, v48, v48
	v_fma_f32 v49, v49, s12, -v50
	v_max_f32_e32 v49, 0, v49
	v_add_f32_e32 v49, 0x3727c5ac, v49
	v_rsq_f32_e32 v50, v49
	v_and_b32_e32 v49, 0xffff0000, v46
	s_ashr_i32 s21, s20, 31
	s_lshl_b64 s[20:21], s[20:21], 12
	v_mul_f32_e64 v54, v48, -v50
	v_lshlrev_b32_e32 v48, 16, v46
	v_lshlrev_b32_e32 v46, 16, v47
	v_and_b32_e32 v47, 0xffff0000, v47
	v_pk_fma_f32 v[56:57], v[50:51], v[48:49], v[54:55] op_sel_hi:[0,1,0]
	v_pk_fma_f32 v[46:47], v[50:51], v[46:47], v[54:55] op_sel_hi:[0,1,0]
	v_pk_fma_f32 v[48:49], v[2:3], v[46:47], v[6:7]
	v_pk_fma_f32 v[46:47], v[0:1], v[56:57], v[4:5]
	v_lshl_add_u64 v[52:53], v[36:37], 0, s[20:21]
	global_store_dwordx4 v[52:53], v[46:49], off
	s_nop 1
	v_lshlrev_b32_e32 v46, 16, v44
	v_and_b32_e32 v47, 0xffff0000, v44
	v_lshlrev_b32_e32 v44, 16, v45
	v_and_b32_e32 v45, 0xffff0000, v45
	v_pk_fma_f32 v[56:57], v[50:51], v[46:47], v[54:55] op_sel_hi:[0,1,0]
	v_pk_fma_f32 v[44:45], v[50:51], v[44:45], v[54:55] op_sel_hi:[0,1,0]
	v_pk_fma_f32 v[46:47], v[10:11], v[44:45], v[18:19]
	v_pk_fma_f32 v[44:45], v[8:9], v[56:57], v[16:17]
	v_lshl_add_u64 v[48:49], v[52:53], 0, s[14:15]
	global_store_dwordx4 v[48:49], v[44:47], off
	s_nop 1
	v_lshlrev_b32_e32 v44, 16, v42
	v_and_b32_e32 v45, 0xffff0000, v42
	v_lshlrev_b32_e32 v42, 16, v43
	v_and_b32_e32 v43, 0xffff0000, v43
	v_pk_fma_f32 v[48:49], v[50:51], v[44:45], v[54:55] op_sel_hi:[0,1,0]
	v_pk_fma_f32 v[42:43], v[50:51], v[42:43], v[54:55] op_sel_hi:[0,1,0]
	v_pk_fma_f32 v[44:45], v[14:15], v[42:43], v[22:23]
	v_pk_fma_f32 v[42:43], v[12:13], v[48:49], v[20:21]
	v_lshl_add_u64 v[46:47], v[52:53], 0, s[16:17]
	global_store_dwordx4 v[46:47], v[42:45], off
	s_nop 1
	v_lshlrev_b32_e32 v42, 16, v40
	v_and_b32_e32 v43, 0xffff0000, v40
	v_lshlrev_b32_e32 v40, 16, v41
	v_and_b32_e32 v41, 0xffff0000, v41
	v_pk_fma_f32 v[46:47], v[50:51], v[42:43], v[54:55] op_sel_hi:[0,1,0]
	v_pk_fma_f32 v[40:41], v[50:51], v[40:41], v[54:55] op_sel_hi:[0,1,0]
	v_lshl_add_u64 v[44:45], v[52:53], 0, s[18:19]
	v_pk_fma_f32 v[42:43], v[26:27], v[40:41], v[30:31]
	v_pk_fma_f32 v[40:41], v[24:25], v[46:47], v[28:29]
	s_nop 0
	global_store_dwordx4 v[44:45], v[40:43], off
	s_nop 1
	s_branch .LBB0_1824
